# SwiGLU epilogues: the 58 hazard pads per epilogue that only guarded the former packed multiplies / already-spaced rcp results removed
# baseline (speedup 1.0000x reference)
; __device__ __forceinline__ unsigned pk2(float lo, float hi) { f32x2_t v = {lo, hi}; bf16x2_t b = __builtin_convertvector(v, bf16x2_t); return __builtin_bit_cast(unsigned, b); }
; #define SWG(a, b) ((a) * (b) * __builtin_amdgcn_rcpf(1.f + __builtin_amdgcn_exp2f(-(a))))
;     __device__ __forceinline__ void operator()(const f32x4 (&acc)[2][2][4][2], const pg8::Unit& u, int wr, int wc, int fr, int fq) const {
;         const int row0 = u.pm * 256 + wr * 64 + fr, col = u.pn * 128 + wc * 32 + 8 * fq;
; #pragma unroll
;         for (int ai = 0; ai < 2; ++ai)
; #pragma unroll
;             for (int m = 0; m < 4; ++m) {
;                 const f32x4 a0 = acc[ai][0][m][0], a1 = acc[ai][0][m][1], b0 = acc[ai][1][m][0], b1 = acc[ai][1][m][1];
;                 u32x4 w;
;     ...
;                 w.x = pk2(SWG(a0[0], b0[0]), SWG(a0[1], b0[1])); w.y = pk2(SWG(a0[2], b0[2]), SWG(a0[3], b0[3]));
;                 w.z = pk2(SWG(a1[0], b1[0]), SWG(a1[1], b1[1])); w.w = pk2(SWG(a1[2], b1[2]), SWG(a1[3], b1[3]));
;     ...
;                 *(u32x4*)(H + (size_t)(row0 + ai * 128 + m * 16) * DFF + col) = w;
;             }
.LBB0_406:
	v_exp_f32_e64 v148, -v122
	v_exp_f32_e64 v149, -v123
	v_mul_f32_e32 v122, v122, v126
	v_mul_f32_e32 v123, v123, v127
	v_mul_f32_e32 v128, v124, v128
	v_mul_f32_e32 v129, v125, v129
	v_add_f32_e32 v148, 1.0, v148
	v_add_f32_e32 v149, 1.0, v149
	v_rcp_f32_e32 v148, v148
	v_rcp_f32_e32 v149, v149
	v_mul_f32_e32 v120, v116, v120
	v_mul_f32_e32 v121, v117, v121
	v_lshl_or_b32 v146, s13, 7, v143
	v_lshl_add_u32 v145, s22, 8, v0
	v_mul_f32_e32 v122, v148, v122
	v_mul_f32_e32 v123, v149, v123
	v_ashrrev_i32_e32 v147, 31, v146
	v_cvt_pk_bf16_f32 v122, v122, v123
	v_exp_f32_e64 v123, -v124
	v_mul_f32_e32 v112, v108, v112
	v_mul_f32_e32 v113, v109, v113
	v_mul_f32_e32 v104, v100, v104
	v_mul_f32_e32 v105, v101, v105
	v_mul_f32_e32 v96, v92, v96
	v_mul_f32_e32 v97, v93, v97
	v_add_f32_e32 v123, 1.0, v123
	v_rcp_f32_e32 v124, v123
	v_exp_f32_e64 v123, -v125
	v_mul_f32_e32 v88, v84, v88
	v_mul_f32_e32 v89, v85, v89
	v_mul_f32_e32 v80, v76, v80
	v_mul_f32_e32 v81, v77, v81
	v_mul_f32_e32 v72, v68, v72
	v_mul_f32_e32 v73, v69, v73
	v_add_f32_e32 v123, 1.0, v123
	v_rcp_f32_e32 v125, v123
	v_mul_f32_e32 v64, v60, v64
	v_mul_f32_e32 v65, v61, v65
	v_mul_f32_e32 v56, v52, v56
	v_mul_f32_e32 v57, v53, v57
	v_mul_f32_e32 v48, v44, v48
	v_mul_f32_e32 v49, v45, v49
	v_mul_f32_e32 v124, v124, v128
	v_mul_f32_e32 v125, v125, v129
	v_mul_f32_e32 v40, v36, v40
	v_mul_f32_e32 v41, v37, v41
	v_cvt_pk_bf16_f32 v123, v124, v125
	v_exp_f32_e64 v124, -v114
	v_exp_f32_e64 v125, -v115
	v_mul_f32_e32 v114, v114, v118
	v_mul_f32_e32 v115, v115, v119
	v_mul_f32_e32 v32, v28, v32
	v_mul_f32_e32 v33, v29, v33
	v_add_f32_e32 v124, 1.0, v124
	v_add_f32_e32 v125, 1.0, v125
	v_rcp_f32_e32 v124, v124
	v_rcp_f32_e32 v125, v125
	v_mul_f32_e32 v24, v20, v24
	v_mul_f32_e32 v25, v21, v25
	v_mul_f32_e32 v16, v12, v16
	v_mul_f32_e32 v17, v13, v17
	v_mul_f32_e32 v8, v4, v8
	v_mul_f32_e32 v9, v5, v9
	v_mul_f32_e32 v114, v124, v114
	v_mul_f32_e32 v115, v125, v115
	s_andn2_b64 vcc, exec, s[36:37]
	v_cvt_pk_bf16_f32 v124, v114, v115
	v_exp_f32_e64 v114, -v116
	v_exp_f32_e64 v115, -v117
	v_lshlrev_b64 v[116:117], 1, v[146:147]
	v_add_f32_e32 v114, 1.0, v114
	v_add_f32_e32 v115, 1.0, v115
	v_rcp_f32_e32 v114, v114
	v_rcp_f32_e32 v115, v115
	v_mul_f32_e32 v114, v114, v120
	v_mul_f32_e32 v115, v115, v121
	v_cvt_pk_bf16_f32 v125, v114, v115
	v_mov_b64_e32 v[114:115], s[30:31]
	v_mad_i64_i32 v[118:119], s[4:5], v145, s16, v[114:115]
	v_lshl_add_u64 v[118:119], v[118:119], 0, v[116:117]
	global_store_dwordx4 v[118:119], v[122:125], off
	v_exp_f32_e64 v118, -v106
	v_exp_f32_e64 v119, -v107
	v_mul_f32_e32 v106, v106, v110
	v_mul_f32_e32 v107, v107, v111
	v_add_f32_e32 v118, 1.0, v118
	v_add_f32_e32 v119, 1.0, v119
	v_rcp_f32_e32 v118, v118
	v_rcp_f32_e32 v119, v119
	v_mul_f32_e32 v106, v118, v106
	v_mul_f32_e32 v107, v119, v107
	v_cvt_pk_bf16_f32 v106, v106, v107
	v_exp_f32_e64 v107, -v108
	s_nop 0
	v_add_f32_e32 v107, 1.0, v107
	v_rcp_f32_e32 v108, v107
	v_exp_f32_e64 v107, -v109
	s_nop 0
	v_add_f32_e32 v107, 1.0, v107
	v_rcp_f32_e32 v109, v107
	v_mul_f32_e32 v108, v108, v112
	v_mul_f32_e32 v109, v109, v113
	v_cvt_pk_bf16_f32 v107, v108, v109
	v_exp_f32_e64 v108, -v98
	v_exp_f32_e64 v109, -v99
	v_mul_f32_e32 v98, v98, v102
	v_mul_f32_e32 v99, v99, v103
	v_add_f32_e32 v108, 1.0, v108
	v_add_f32_e32 v109, 1.0, v109
	v_rcp_f32_e32 v108, v108
	v_rcp_f32_e32 v109, v109
	v_mul_f32_e32 v98, v108, v98
	v_mul_f32_e32 v99, v109, v99
	v_cvt_pk_bf16_f32 v108, v98, v99
	v_exp_f32_e64 v98, -v100
	v_exp_f32_e64 v99, -v101
	v_add_f32_e32 v98, 1.0, v98
	v_add_f32_e32 v99, 1.0, v99
	v_rcp_f32_e32 v98, v98
	v_rcp_f32_e32 v99, v99
	v_mul_f32_e32 v98, v98, v104
	v_mul_f32_e32 v99, v99, v105
	v_cvt_pk_bf16_f32 v109, v98, v99
	v_or_b32_e32 v98, 16, v145
	v_mad_i64_i32 v[98:99], s[4:5], v98, s16, v[114:115]
	v_lshl_add_u64 v[98:99], v[98:99], 0, v[116:117]
	global_store_dwordx4 v[98:99], v[106:109], off
	v_exp_f32_e64 v98, -v90
	v_exp_f32_e64 v99, -v91
	v_mul_f32_e32 v90, v90, v94
	v_mul_f32_e32 v91, v91, v95
	v_add_f32_e32 v98, 1.0, v98
	v_add_f32_e32 v99, 1.0, v99
	v_rcp_f32_e32 v98, v98
	v_rcp_f32_e32 v99, v99
	v_mul_f32_e32 v90, v98, v90
	v_mul_f32_e32 v91, v99, v91
	v_cvt_pk_bf16_f32 v90, v90, v91
	v_exp_f32_e64 v91, -v92
	s_nop 0
	v_add_f32_e32 v91, 1.0, v91
	v_rcp_f32_e32 v92, v91
	v_exp_f32_e64 v91, -v93
	s_nop 0
	v_add_f32_e32 v91, 1.0, v91
	v_rcp_f32_e32 v93, v91
	v_mul_f32_e32 v92, v92, v96
	v_mul_f32_e32 v93, v93, v97
	v_cvt_pk_bf16_f32 v91, v92, v93
	v_exp_f32_e64 v92, -v82
	v_exp_f32_e64 v93, -v83
	v_mul_f32_e32 v82, v82, v86
	v_mul_f32_e32 v83, v83, v87
	v_add_f32_e32 v92, 1.0, v92
	v_add_f32_e32 v93, 1.0, v93
	v_rcp_f32_e32 v92, v92
	v_rcp_f32_e32 v93, v93
	v_mul_f32_e32 v82, v92, v82
	v_mul_f32_e32 v83, v93, v83
	v_cvt_pk_bf16_f32 v92, v82, v83
	v_exp_f32_e64 v82, -v84
	v_exp_f32_e64 v83, -v85
	v_add_f32_e32 v82, 1.0, v82
	v_add_f32_e32 v83, 1.0, v83
	v_rcp_f32_e32 v82, v82
	v_rcp_f32_e32 v83, v83
	v_mul_f32_e32 v82, v82, v88
	v_mul_f32_e32 v83, v83, v89
	v_cvt_pk_bf16_f32 v93, v82, v83
	v_or_b32_e32 v82, 32, v145
	v_mad_i64_i32 v[82:83], s[4:5], v82, s16, v[114:115]
	v_lshl_add_u64 v[82:83], v[82:83], 0, v[116:117]
	global_store_dwordx4 v[82:83], v[90:93], off
	v_exp_f32_e64 v82, -v74
	v_exp_f32_e64 v83, -v75
	v_mul_f32_e32 v74, v74, v78
	v_mul_f32_e32 v75, v75, v79
	v_add_f32_e32 v82, 1.0, v82
	v_add_f32_e32 v83, 1.0, v83
	v_rcp_f32_e32 v82, v82
	v_rcp_f32_e32 v83, v83
	v_mul_f32_e32 v74, v82, v74
	v_mul_f32_e32 v75, v83, v75
	v_cvt_pk_bf16_f32 v74, v74, v75
	v_exp_f32_e64 v75, -v76
	s_nop 0
	v_add_f32_e32 v75, 1.0, v75
	v_rcp_f32_e32 v76, v75
	v_exp_f32_e64 v75, -v77
	s_nop 0
	v_add_f32_e32 v75, 1.0, v75
; __device__ __forceinline__ unsigned pk2(float lo, float hi) { f32x2_t v = {lo, hi}; bf16x2_t b = __builtin_convertvector(v, bf16x2_t); return __builtin_bit_cast(unsigned, b); }
; #define SWG(a, b) ((a) * (b) * __builtin_amdgcn_rcpf(1.f + __builtin_amdgcn_exp2f(-(a))))
;     __device__ __forceinline__ void operator()(const f32x4 (&acc)[2][2][4][2], const pg8::Unit& u, int wr, int wc, int fr, int fq) const {
;         const int row0 = u.pm * 256 + wr * 64 + fr, col = u.pn * 128 + wc * 32 + 8 * fq;
; #pragma unroll
;         for (int ai = 0; ai < 2; ++ai)
; #pragma unroll
;             for (int m = 0; m < 4; ++m) {
;                 const f32x4 a0 = acc[ai][0][m][0], a1 = acc[ai][0][m][1], b0 = acc[ai][1][m][0], b1 = acc[ai][1][m][1];
;                 u32x4 w;
;     ...
;                 w.x = pk2(SWG(a0[0], b0[0]), SWG(a0[1], b0[1])); w.y = pk2(SWG(a0[2], b0[2]), SWG(a0[3], b0[3]));
;                 w.z = pk2(SWG(a1[0], b1[0]), SWG(a1[1], b1[1])); w.w = pk2(SWG(a1[2], b1[2]), SWG(a1[3], b1[3]));
;     ...
;                 *(u32x4*)(H + (size_t)(row0 + ai * 128 + m * 16) * DFF + col) = w;
;             }
	v_rcp_f32_e32 v77, v75
	v_mul_f32_e32 v76, v76, v80
	v_mul_f32_e32 v77, v77, v81
	v_cvt_pk_bf16_f32 v75, v76, v77
	v_exp_f32_e64 v76, -v66
	v_exp_f32_e64 v77, -v67
	v_mul_f32_e32 v66, v66, v70
	v_mul_f32_e32 v67, v67, v71
	v_add_f32_e32 v76, 1.0, v76
	v_add_f32_e32 v77, 1.0, v77
	v_rcp_f32_e32 v76, v76
	v_rcp_f32_e32 v77, v77
	v_mul_f32_e32 v66, v76, v66
	v_mul_f32_e32 v67, v77, v67
	v_cvt_pk_bf16_f32 v76, v66, v67
	v_exp_f32_e64 v66, -v68
	v_exp_f32_e64 v67, -v69
	v_add_u32_e32 v68, 0x80, v145
	v_add_f32_e32 v66, 1.0, v66
	v_add_f32_e32 v67, 1.0, v67
	v_rcp_f32_e32 v66, v66
	v_rcp_f32_e32 v67, v67
	v_mul_f32_e32 v66, v66, v72
	v_mul_f32_e32 v67, v67, v73
	v_cvt_pk_bf16_f32 v77, v66, v67
	v_or_b32_e32 v66, 48, v145
	v_mad_i64_i32 v[66:67], s[4:5], v66, s16, v[114:115]
	v_lshl_add_u64 v[66:67], v[66:67], 0, v[116:117]
	global_store_dwordx4 v[66:67], v[74:77], off
	v_exp_f32_e64 v66, -v58
	v_exp_f32_e64 v67, -v59
	v_mul_f32_e32 v58, v58, v62
	v_mul_f32_e32 v59, v59, v63
	v_add_f32_e32 v66, 1.0, v66
	v_add_f32_e32 v67, 1.0, v67
	v_rcp_f32_e32 v66, v66
	v_rcp_f32_e32 v67, v67
	v_mul_f32_e32 v58, v66, v58
	v_mul_f32_e32 v59, v67, v59
	v_cvt_pk_bf16_f32 v58, v58, v59
	v_exp_f32_e64 v59, -v60
	s_nop 0
	v_add_f32_e32 v59, 1.0, v59
	v_rcp_f32_e32 v60, v59
	v_exp_f32_e64 v59, -v61
	s_nop 0
	v_add_f32_e32 v59, 1.0, v59
	v_rcp_f32_e32 v61, v59
	v_mul_f32_e32 v60, v60, v64
	v_mul_f32_e32 v61, v61, v65
	v_cvt_pk_bf16_f32 v59, v60, v61
	v_exp_f32_e64 v60, -v50
	v_exp_f32_e64 v61, -v51
	v_mul_f32_e32 v50, v50, v54
	v_mul_f32_e32 v51, v51, v55
	v_add_f32_e32 v60, 1.0, v60
	v_add_f32_e32 v61, 1.0, v61
	v_rcp_f32_e32 v60, v60
	v_rcp_f32_e32 v61, v61
	v_mul_f32_e32 v50, v60, v50
	v_mul_f32_e32 v51, v61, v51
	v_cvt_pk_bf16_f32 v60, v50, v51
	v_exp_f32_e64 v50, -v52
	v_exp_f32_e64 v51, -v53
	v_add_f32_e32 v50, 1.0, v50
	v_add_f32_e32 v51, 1.0, v51
	v_rcp_f32_e32 v50, v50
	v_rcp_f32_e32 v51, v51
	v_mul_f32_e32 v50, v50, v56
	v_mul_f32_e32 v51, v51, v57
	v_cvt_pk_bf16_f32 v61, v50, v51
	v_mad_i64_i32 v[50:51], s[4:5], v68, s16, v[114:115]
	v_lshl_add_u64 v[50:51], v[50:51], 0, v[116:117]
	global_store_dwordx4 v[50:51], v[58:61], off
	v_exp_f32_e64 v50, -v42
	v_exp_f32_e64 v51, -v43
	v_mul_f32_e32 v42, v42, v46
	v_mul_f32_e32 v43, v43, v47
	v_add_f32_e32 v50, 1.0, v50
	v_add_f32_e32 v51, 1.0, v51
	v_rcp_f32_e32 v50, v50
	v_rcp_f32_e32 v51, v51
	v_mul_f32_e32 v42, v50, v42
	v_mul_f32_e32 v43, v51, v43
	v_cvt_pk_bf16_f32 v42, v42, v43
	v_exp_f32_e64 v43, -v44
	s_nop 0
	v_add_f32_e32 v43, 1.0, v43
	v_rcp_f32_e32 v44, v43
	v_exp_f32_e64 v43, -v45
	s_nop 0
	v_add_f32_e32 v43, 1.0, v43
	v_rcp_f32_e32 v45, v43
	v_mul_f32_e32 v44, v44, v48
	v_mul_f32_e32 v45, v45, v49
	v_cvt_pk_bf16_f32 v43, v44, v45
	v_exp_f32_e64 v44, -v34
	v_exp_f32_e64 v45, -v35
	v_mul_f32_e32 v34, v34, v38
	v_mul_f32_e32 v35, v35, v39
	v_add_f32_e32 v44, 1.0, v44
	v_add_f32_e32 v45, 1.0, v45
	v_rcp_f32_e32 v44, v44
	v_rcp_f32_e32 v45, v45
	v_mul_f32_e32 v34, v44, v34
	v_mul_f32_e32 v35, v45, v35
	v_cvt_pk_bf16_f32 v44, v34, v35
	v_exp_f32_e64 v34, -v36
	v_exp_f32_e64 v35, -v37
	v_add_f32_e32 v34, 1.0, v34
	v_add_f32_e32 v35, 1.0, v35
	v_rcp_f32_e32 v34, v34
	v_rcp_f32_e32 v35, v35
	v_mul_f32_e32 v34, v34, v40
	v_mul_f32_e32 v35, v35, v41
	v_cvt_pk_bf16_f32 v45, v34, v35
	v_add_u32_e32 v34, 0x90, v145
	v_mad_i64_i32 v[34:35], s[4:5], v34, s16, v[114:115]
	v_lshl_add_u64 v[34:35], v[34:35], 0, v[116:117]
	global_store_dwordx4 v[34:35], v[42:45], off
	v_exp_f32_e64 v34, -v26
	v_exp_f32_e64 v35, -v27
	v_mul_f32_e32 v26, v26, v30
	v_mul_f32_e32 v27, v27, v31
	v_add_f32_e32 v34, 1.0, v34
	v_add_f32_e32 v35, 1.0, v35
	v_rcp_f32_e32 v34, v34
	v_rcp_f32_e32 v35, v35
	v_mul_f32_e32 v26, v34, v26
	v_mul_f32_e32 v27, v35, v27
	v_cvt_pk_bf16_f32 v26, v26, v27
	v_exp_f32_e64 v27, -v28
	s_nop 0
	v_add_f32_e32 v27, 1.0, v27
	v_rcp_f32_e32 v28, v27
	v_exp_f32_e64 v27, -v29
	s_nop 0
	v_add_f32_e32 v27, 1.0, v27
	v_rcp_f32_e32 v29, v27
	v_mul_f32_e32 v28, v28, v32
	v_mul_f32_e32 v29, v29, v33
	v_cvt_pk_bf16_f32 v27, v28, v29
	v_exp_f32_e64 v28, -v18
	v_exp_f32_e64 v29, -v19
	v_mul_f32_e32 v18, v18, v22
	v_mul_f32_e32 v19, v19, v23
	v_add_f32_e32 v28, 1.0, v28
	v_add_f32_e32 v29, 1.0, v29
	v_rcp_f32_e32 v28, v28
	v_rcp_f32_e32 v29, v29
	v_mul_f32_e32 v18, v28, v18
	v_mul_f32_e32 v19, v29, v19
	v_cvt_pk_bf16_f32 v28, v18, v19
	v_exp_f32_e64 v18, -v20
	v_exp_f32_e64 v19, -v21
	v_add_f32_e32 v18, 1.0, v18
	v_add_f32_e32 v19, 1.0, v19
	v_rcp_f32_e32 v18, v18
	v_rcp_f32_e32 v19, v19
	v_mul_f32_e32 v18, v18, v24
	v_mul_f32_e32 v19, v19, v25
	v_cvt_pk_bf16_f32 v29, v18, v19
	v_add_u32_e32 v18, 0xa0, v145
	v_mad_i64_i32 v[18:19], s[4:5], v18, s16, v[114:115]
	v_lshl_add_u64 v[18:19], v[18:19], 0, v[116:117]
	global_store_dwordx4 v[18:19], v[26:29], off
	v_exp_f32_e64 v18, -v10
	v_exp_f32_e64 v19, -v11
	v_mul_f32_e32 v10, v10, v14
	v_mul_f32_e32 v11, v11, v15
	v_add_f32_e32 v18, 1.0, v18
	v_add_f32_e32 v19, 1.0, v19
	v_rcp_f32_e32 v18, v18
	v_rcp_f32_e32 v19, v19
	v_mul_f32_e32 v10, v18, v10
	v_mul_f32_e32 v11, v19, v11
	v_cvt_pk_bf16_f32 v10, v10, v11
	v_exp_f32_e64 v11, -v12
	s_nop 0
	v_add_f32_e32 v11, 1.0, v11
	v_rcp_f32_e32 v12, v11
	v_exp_f32_e64 v11, -v13
	s_nop 0
	v_add_f32_e32 v11, 1.0, v11
	v_rcp_f32_e32 v13, v11
	v_mul_f32_e32 v12, v12, v16
	v_mul_f32_e32 v13, v13, v17
	v_cvt_pk_bf16_f32 v11, v12, v13
	v_exp_f32_e64 v12, -v2
	v_exp_f32_e64 v13, -v3
	v_mul_f32_e32 v2, v2, v6
	v_mul_f32_e32 v3, v3, v7
	v_add_f32_e32 v12, 1.0, v12
	v_add_f32_e32 v13, 1.0, v13
	v_rcp_f32_e32 v12, v12
	v_rcp_f32_e32 v13, v13
	v_mul_f32_e32 v2, v12, v2
	v_mul_f32_e32 v3, v13, v3
	v_cvt_pk_bf16_f32 v12, v2, v3
	v_exp_f32_e64 v2, -v4
	v_exp_f32_e64 v3, -v5
	v_add_f32_e32 v2, 1.0, v2
	v_add_f32_e32 v3, 1.0, v3
	v_rcp_f32_e32 v2, v2
	v_rcp_f32_e32 v3, v3
	v_mul_f32_e32 v2, v2, v8
	v_mul_f32_e32 v3, v3, v9
	v_cvt_pk_bf16_f32 v13, v2, v3
	v_add_u32_e32 v2, 0xb0, v145
	v_mad_i64_i32 v[2:3], s[4:5], v2, s16, v[114:115]
	v_lshl_add_u64 v[2:3], v[2:3], 0, v[116:117]
	s_mov_b64 s[4:5], -1
	global_store_dwordx4 v[2:3], v[10:13], off
	s_cbranch_vccnz .LBB0_399
	s_andn2_b64 vcc, exec, s[38:39]
	s_cbranch_vccnz .LBB0_398
	s_barrier
	s_branch .LBB0_398

; __device__ __forceinline__ unsigned pk2(float lo, float hi) { f32x2_t v = {lo, hi}; bf16x2_t b = __builtin_convertvector(v, bf16x2_t); return __builtin_bit_cast(unsigned, b); }
; #define SWG(a, b) ((a) * (b) * __builtin_amdgcn_rcpf(1.f + __builtin_amdgcn_exp2f(-(a))))
;     __device__ __forceinline__ void operator()(const f32x4 (&acc)[2][2][4][2], const pg8::Unit& u, int wr, int wc, int fr, int fq) const {
;         const int row0 = u.pm * 256 + wr * 64 + fr, col = u.pn * 128 + wc * 32 + 8 * fq;
; #pragma unroll
;         for (int ai = 0; ai < 2; ++ai)
; #pragma unroll
;             for (int m = 0; m < 4; ++m) {
;                 const f32x4 a0 = acc[ai][0][m][0], a1 = acc[ai][0][m][1], b0 = acc[ai][1][m][0], b1 = acc[ai][1][m][1];
;                 u32x4 w;
;     ...
;                 w.x = pk2(SWG(a0[0], b0[0]), SWG(a0[1], b0[1])); w.y = pk2(SWG(a0[2], b0[2]), SWG(a0[3], b0[3]));
;                 w.z = pk2(SWG(a1[0], b1[0]), SWG(a1[1], b1[1])); w.w = pk2(SWG(a1[2], b1[2]), SWG(a1[3], b1[3]));
;     ...
;                 *(u32x4*)(H + (size_t)(row0 + ai * 128 + m * 16) * DFF + col) = w;
;             }
.LBB0_1667:
	v_exp_f32_e64 v148, -v122
	v_exp_f32_e64 v149, -v123
	v_mul_f32_e32 v122, v122, v126
	v_mul_f32_e32 v123, v123, v127
	v_mul_f32_e32 v128, v124, v128
	v_mul_f32_e32 v129, v125, v129
	v_add_f32_e32 v148, 1.0, v148
	v_add_f32_e32 v149, 1.0, v149
	v_rcp_f32_e32 v148, v148
	v_rcp_f32_e32 v149, v149
	v_mul_f32_e32 v120, v116, v120
	v_mul_f32_e32 v121, v117, v121
	v_lshl_or_b32 v146, s13, 7, v143
	v_lshl_add_u32 v145, s48, 8, v0
	v_mul_f32_e32 v122, v148, v122
	v_mul_f32_e32 v123, v149, v123
	v_ashrrev_i32_e32 v147, 31, v146
	v_cvt_pk_bf16_f32 v122, v122, v123
	v_exp_f32_e64 v123, -v124
	v_mul_f32_e32 v112, v108, v112
	v_mul_f32_e32 v113, v109, v113
	v_mul_f32_e32 v104, v100, v104
	v_mul_f32_e32 v105, v101, v105
	v_mul_f32_e32 v96, v92, v96
	v_mul_f32_e32 v97, v93, v97
	v_add_f32_e32 v123, 1.0, v123
	v_rcp_f32_e32 v124, v123
	v_exp_f32_e64 v123, -v125
	v_mul_f32_e32 v88, v84, v88
	v_mul_f32_e32 v89, v85, v89
	v_mul_f32_e32 v80, v76, v80
	v_mul_f32_e32 v81, v77, v81
	v_mul_f32_e32 v72, v68, v72
	v_mul_f32_e32 v73, v69, v73
	v_add_f32_e32 v123, 1.0, v123
	v_rcp_f32_e32 v125, v123
	v_mul_f32_e32 v64, v60, v64
	v_mul_f32_e32 v65, v61, v65
	v_mul_f32_e32 v56, v52, v56
	v_mul_f32_e32 v57, v53, v57
	v_mul_f32_e32 v48, v44, v48
	v_mul_f32_e32 v49, v45, v49
	v_mul_f32_e32 v124, v124, v128
	v_mul_f32_e32 v125, v125, v129
	v_mul_f32_e32 v40, v36, v40
	v_mul_f32_e32 v41, v37, v41
	v_cvt_pk_bf16_f32 v123, v124, v125
	v_exp_f32_e64 v124, -v114
	v_exp_f32_e64 v125, -v115
	v_mul_f32_e32 v114, v114, v118
	v_mul_f32_e32 v115, v115, v119
	v_mul_f32_e32 v32, v28, v32
	v_mul_f32_e32 v33, v29, v33
	v_add_f32_e32 v124, 1.0, v124
	v_add_f32_e32 v125, 1.0, v125
	v_rcp_f32_e32 v124, v124
	v_rcp_f32_e32 v125, v125
	v_mul_f32_e32 v24, v20, v24
	v_mul_f32_e32 v25, v21, v25
	v_mul_f32_e32 v16, v12, v16
	v_mul_f32_e32 v17, v13, v17
	v_mul_f32_e32 v8, v4, v8
	v_mul_f32_e32 v9, v5, v9
	v_mul_f32_e32 v114, v124, v114
	v_mul_f32_e32 v115, v125, v115
	s_andn2_b64 vcc, exec, s[38:39]
	v_cvt_pk_bf16_f32 v124, v114, v115
	v_exp_f32_e64 v114, -v116
	v_exp_f32_e64 v115, -v117
	v_lshlrev_b64 v[116:117], 1, v[146:147]
	s_mov_b32 s33, 0x10000
	v_add_f32_e32 v114, 1.0, v114
	v_add_f32_e32 v115, 1.0, v115
	v_rcp_f32_e32 v114, v114
	v_rcp_f32_e32 v115, v115
	v_mul_f32_e32 v114, v114, v120
	v_mul_f32_e32 v115, v115, v121
	v_cvt_pk_bf16_f32 v125, v114, v115
	v_mov_b64_e32 v[114:115], s[30:31]
	v_mad_i64_i32 v[118:119], s[4:5], v145, s16, v[114:115]
	v_lshl_add_u64 v[118:119], v[118:119], 0, v[116:117]
	global_store_dwordx4 v[118:119], v[122:125], off
	v_exp_f32_e64 v118, -v106
	v_exp_f32_e64 v119, -v107
	v_mul_f32_e32 v106, v106, v110
	v_mul_f32_e32 v107, v107, v111
	v_add_f32_e32 v118, 1.0, v118
	v_add_f32_e32 v119, 1.0, v119
	v_rcp_f32_e32 v118, v118
	v_rcp_f32_e32 v119, v119
	v_mul_f32_e32 v106, v118, v106
	v_mul_f32_e32 v107, v119, v107
	v_cvt_pk_bf16_f32 v106, v106, v107
	v_exp_f32_e64 v107, -v108
	s_nop 0
	v_add_f32_e32 v107, 1.0, v107
	v_rcp_f32_e32 v108, v107
	v_exp_f32_e64 v107, -v109
	s_nop 0
	v_add_f32_e32 v107, 1.0, v107
	v_rcp_f32_e32 v109, v107
	v_mul_f32_e32 v108, v108, v112
	v_mul_f32_e32 v109, v109, v113
	v_cvt_pk_bf16_f32 v107, v108, v109
	v_exp_f32_e64 v108, -v98
	v_exp_f32_e64 v109, -v99
	v_mul_f32_e32 v98, v98, v102
	v_mul_f32_e32 v99, v99, v103
	v_add_f32_e32 v108, 1.0, v108
	v_add_f32_e32 v109, 1.0, v109
	v_rcp_f32_e32 v108, v108
	v_rcp_f32_e32 v109, v109
	v_mul_f32_e32 v98, v108, v98
	v_mul_f32_e32 v99, v109, v99
	v_cvt_pk_bf16_f32 v108, v98, v99
	v_exp_f32_e64 v98, -v100
	v_exp_f32_e64 v99, -v101
	v_add_f32_e32 v98, 1.0, v98
	v_add_f32_e32 v99, 1.0, v99
	v_rcp_f32_e32 v98, v98
	v_rcp_f32_e32 v99, v99
	v_mul_f32_e32 v98, v98, v104
	v_mul_f32_e32 v99, v99, v105
	v_cvt_pk_bf16_f32 v109, v98, v99
	v_or_b32_e32 v98, 16, v145
	v_mad_i64_i32 v[98:99], s[4:5], v98, s16, v[114:115]
	v_lshl_add_u64 v[98:99], v[98:99], 0, v[116:117]
	global_store_dwordx4 v[98:99], v[106:109], off
	v_exp_f32_e64 v98, -v90
	v_exp_f32_e64 v99, -v91
	v_mul_f32_e32 v90, v90, v94
	v_mul_f32_e32 v91, v91, v95
	v_add_f32_e32 v98, 1.0, v98
	v_add_f32_e32 v99, 1.0, v99
	v_rcp_f32_e32 v98, v98
	v_rcp_f32_e32 v99, v99
	v_mul_f32_e32 v90, v98, v90
	v_mul_f32_e32 v91, v99, v91
	v_cvt_pk_bf16_f32 v90, v90, v91
	v_exp_f32_e64 v91, -v92
	s_nop 0
	v_add_f32_e32 v91, 1.0, v91
	v_rcp_f32_e32 v92, v91
	v_exp_f32_e64 v91, -v93
	s_nop 0
	v_add_f32_e32 v91, 1.0, v91
	v_rcp_f32_e32 v93, v91
	v_mul_f32_e32 v92, v92, v96
	v_mul_f32_e32 v93, v93, v97
	v_cvt_pk_bf16_f32 v91, v92, v93
	v_exp_f32_e64 v92, -v82
	v_exp_f32_e64 v93, -v83
	v_mul_f32_e32 v82, v82, v86
	v_mul_f32_e32 v83, v83, v87
	v_add_f32_e32 v92, 1.0, v92
	v_add_f32_e32 v93, 1.0, v93
	v_rcp_f32_e32 v92, v92
	v_rcp_f32_e32 v93, v93
	v_mul_f32_e32 v82, v92, v82
	v_mul_f32_e32 v83, v93, v83
	v_cvt_pk_bf16_f32 v92, v82, v83
	v_exp_f32_e64 v82, -v84
	v_exp_f32_e64 v83, -v85
	v_add_f32_e32 v82, 1.0, v82
	v_add_f32_e32 v83, 1.0, v83
	v_rcp_f32_e32 v82, v82
	v_rcp_f32_e32 v83, v83
	v_mul_f32_e32 v82, v82, v88
	v_mul_f32_e32 v83, v83, v89
	v_cvt_pk_bf16_f32 v93, v82, v83
	v_or_b32_e32 v82, 32, v145
	v_mad_i64_i32 v[82:83], s[4:5], v82, s16, v[114:115]
	v_lshl_add_u64 v[82:83], v[82:83], 0, v[116:117]
	global_store_dwordx4 v[82:83], v[90:93], off
	v_exp_f32_e64 v82, -v74
	v_exp_f32_e64 v83, -v75
	v_mul_f32_e32 v74, v74, v78
	v_mul_f32_e32 v75, v75, v79
	v_add_f32_e32 v82, 1.0, v82
	v_add_f32_e32 v83, 1.0, v83
	v_rcp_f32_e32 v82, v82
	v_rcp_f32_e32 v83, v83
	v_mul_f32_e32 v74, v82, v74
	v_mul_f32_e32 v75, v83, v75
	v_cvt_pk_bf16_f32 v74, v74, v75
	v_exp_f32_e64 v75, -v76
	s_nop 0
	v_add_f32_e32 v75, 1.0, v75
	v_rcp_f32_e32 v76, v75
	v_exp_f32_e64 v75, -v77
; __device__ __forceinline__ unsigned pk2(float lo, float hi) { f32x2_t v = {lo, hi}; bf16x2_t b = __builtin_convertvector(v, bf16x2_t); return __builtin_bit_cast(unsigned, b); }
; #define SWG(a, b) ((a) * (b) * __builtin_amdgcn_rcpf(1.f + __builtin_amdgcn_exp2f(-(a))))
;     __device__ __forceinline__ void operator()(const f32x4 (&acc)[2][2][4][2], const pg8::Unit& u, int wr, int wc, int fr, int fq) const {
;         const int row0 = u.pm * 256 + wr * 64 + fr, col = u.pn * 128 + wc * 32 + 8 * fq;
; #pragma unroll
;         for (int ai = 0; ai < 2; ++ai)
; #pragma unroll
;             for (int m = 0; m < 4; ++m) {
;                 const f32x4 a0 = acc[ai][0][m][0], a1 = acc[ai][0][m][1], b0 = acc[ai][1][m][0], b1 = acc[ai][1][m][1];
;                 u32x4 w;
;     ...
;                 w.x = pk2(SWG(a0[0], b0[0]), SWG(a0[1], b0[1])); w.y = pk2(SWG(a0[2], b0[2]), SWG(a0[3], b0[3]));
;                 w.z = pk2(SWG(a1[0], b1[0]), SWG(a1[1], b1[1])); w.w = pk2(SWG(a1[2], b1[2]), SWG(a1[3], b1[3]));
;     ...
;                 *(u32x4*)(H + (size_t)(row0 + ai * 128 + m * 16) * DFF + col) = w;
;             }
	s_nop 0
	v_add_f32_e32 v75, 1.0, v75
	v_rcp_f32_e32 v77, v75
	v_mul_f32_e32 v76, v76, v80
	v_mul_f32_e32 v77, v77, v81
	v_cvt_pk_bf16_f32 v75, v76, v77
	v_exp_f32_e64 v76, -v66
	v_exp_f32_e64 v77, -v67
	v_mul_f32_e32 v66, v66, v70
	v_mul_f32_e32 v67, v67, v71
	v_add_f32_e32 v76, 1.0, v76
	v_add_f32_e32 v77, 1.0, v77
	v_rcp_f32_e32 v76, v76
	v_rcp_f32_e32 v77, v77
	v_mul_f32_e32 v66, v76, v66
	v_mul_f32_e32 v67, v77, v67
	v_cvt_pk_bf16_f32 v76, v66, v67
	v_exp_f32_e64 v66, -v68
	v_exp_f32_e64 v67, -v69
	v_add_u32_e32 v68, 0x80, v145
	v_add_f32_e32 v66, 1.0, v66
	v_add_f32_e32 v67, 1.0, v67
	v_rcp_f32_e32 v66, v66
	v_rcp_f32_e32 v67, v67
	v_mul_f32_e32 v66, v66, v72
	v_mul_f32_e32 v67, v67, v73
	v_cvt_pk_bf16_f32 v77, v66, v67
	v_or_b32_e32 v66, 48, v145
	v_mad_i64_i32 v[66:67], s[4:5], v66, s16, v[114:115]
	v_lshl_add_u64 v[66:67], v[66:67], 0, v[116:117]
	global_store_dwordx4 v[66:67], v[74:77], off
	v_exp_f32_e64 v66, -v58
	v_exp_f32_e64 v67, -v59
	v_mul_f32_e32 v58, v58, v62
	v_mul_f32_e32 v59, v59, v63
	v_add_f32_e32 v66, 1.0, v66
	v_add_f32_e32 v67, 1.0, v67
	v_rcp_f32_e32 v66, v66
	v_rcp_f32_e32 v67, v67
	v_mul_f32_e32 v58, v66, v58
	v_mul_f32_e32 v59, v67, v59
	v_cvt_pk_bf16_f32 v58, v58, v59
	v_exp_f32_e64 v59, -v60
	s_nop 0
	v_add_f32_e32 v59, 1.0, v59
	v_rcp_f32_e32 v60, v59
	v_exp_f32_e64 v59, -v61
	s_nop 0
	v_add_f32_e32 v59, 1.0, v59
	v_rcp_f32_e32 v61, v59
	v_mul_f32_e32 v60, v60, v64
	v_mul_f32_e32 v61, v61, v65
	v_cvt_pk_bf16_f32 v59, v60, v61
	v_exp_f32_e64 v60, -v50
	v_exp_f32_e64 v61, -v51
	v_mul_f32_e32 v50, v50, v54
	v_mul_f32_e32 v51, v51, v55
	v_add_f32_e32 v60, 1.0, v60
	v_add_f32_e32 v61, 1.0, v61
	v_rcp_f32_e32 v60, v60
	v_rcp_f32_e32 v61, v61
	v_mul_f32_e32 v50, v60, v50
	v_mul_f32_e32 v51, v61, v51
	v_cvt_pk_bf16_f32 v60, v50, v51
	v_exp_f32_e64 v50, -v52
	v_exp_f32_e64 v51, -v53
	v_add_f32_e32 v50, 1.0, v50
	v_add_f32_e32 v51, 1.0, v51
	v_rcp_f32_e32 v50, v50
	v_rcp_f32_e32 v51, v51
	v_mul_f32_e32 v50, v50, v56
	v_mul_f32_e32 v51, v51, v57
	v_cvt_pk_bf16_f32 v61, v50, v51
	v_mad_i64_i32 v[50:51], s[4:5], v68, s16, v[114:115]
	v_lshl_add_u64 v[50:51], v[50:51], 0, v[116:117]
	global_store_dwordx4 v[50:51], v[58:61], off
	v_exp_f32_e64 v50, -v42
	v_exp_f32_e64 v51, -v43
	v_mul_f32_e32 v42, v42, v46
	v_mul_f32_e32 v43, v43, v47
	v_add_f32_e32 v50, 1.0, v50
	v_add_f32_e32 v51, 1.0, v51
	v_rcp_f32_e32 v50, v50
	v_rcp_f32_e32 v51, v51
	v_mul_f32_e32 v42, v50, v42
	v_mul_f32_e32 v43, v51, v43
	v_cvt_pk_bf16_f32 v42, v42, v43
	v_exp_f32_e64 v43, -v44
	s_nop 0
	v_add_f32_e32 v43, 1.0, v43
	v_rcp_f32_e32 v44, v43
	v_exp_f32_e64 v43, -v45
	s_nop 0
	v_add_f32_e32 v43, 1.0, v43
	v_rcp_f32_e32 v45, v43
	v_mul_f32_e32 v44, v44, v48
	v_mul_f32_e32 v45, v45, v49
	v_cvt_pk_bf16_f32 v43, v44, v45
	v_exp_f32_e64 v44, -v34
	v_exp_f32_e64 v45, -v35
	v_mul_f32_e32 v34, v34, v38
	v_mul_f32_e32 v35, v35, v39
	v_add_f32_e32 v44, 1.0, v44
	v_add_f32_e32 v45, 1.0, v45
	v_rcp_f32_e32 v44, v44
	v_rcp_f32_e32 v45, v45
	v_mul_f32_e32 v34, v44, v34
	v_mul_f32_e32 v35, v45, v35
	v_cvt_pk_bf16_f32 v44, v34, v35
	v_exp_f32_e64 v34, -v36
	v_exp_f32_e64 v35, -v37
	v_add_f32_e32 v34, 1.0, v34
	v_add_f32_e32 v35, 1.0, v35
	v_rcp_f32_e32 v34, v34
	v_rcp_f32_e32 v35, v35
	v_mul_f32_e32 v34, v34, v40
	v_mul_f32_e32 v35, v35, v41
	v_cvt_pk_bf16_f32 v45, v34, v35
	v_add_u32_e32 v34, 0x90, v145
	v_mad_i64_i32 v[34:35], s[4:5], v34, s16, v[114:115]
	v_lshl_add_u64 v[34:35], v[34:35], 0, v[116:117]
	global_store_dwordx4 v[34:35], v[42:45], off
	v_exp_f32_e64 v34, -v26
	v_exp_f32_e64 v35, -v27
	v_mul_f32_e32 v26, v26, v30
	v_mul_f32_e32 v27, v27, v31
	v_add_f32_e32 v34, 1.0, v34
	v_add_f32_e32 v35, 1.0, v35
	v_rcp_f32_e32 v34, v34
	v_rcp_f32_e32 v35, v35
	v_mul_f32_e32 v26, v34, v26
	v_mul_f32_e32 v27, v35, v27
	v_cvt_pk_bf16_f32 v26, v26, v27
	v_exp_f32_e64 v27, -v28
	s_nop 0
	v_add_f32_e32 v27, 1.0, v27
	v_rcp_f32_e32 v28, v27
	v_exp_f32_e64 v27, -v29
	s_nop 0
	v_add_f32_e32 v27, 1.0, v27
	v_rcp_f32_e32 v29, v27
	v_mul_f32_e32 v28, v28, v32
	v_mul_f32_e32 v29, v29, v33
	v_cvt_pk_bf16_f32 v27, v28, v29
	v_exp_f32_e64 v28, -v18
	v_exp_f32_e64 v29, -v19
	v_mul_f32_e32 v18, v18, v22
	v_mul_f32_e32 v19, v19, v23
	v_add_f32_e32 v28, 1.0, v28
	v_add_f32_e32 v29, 1.0, v29
	v_rcp_f32_e32 v28, v28
	v_rcp_f32_e32 v29, v29
	v_mul_f32_e32 v18, v28, v18
	v_mul_f32_e32 v19, v29, v19
	v_cvt_pk_bf16_f32 v28, v18, v19
	v_exp_f32_e64 v18, -v20
	v_exp_f32_e64 v19, -v21
	v_add_f32_e32 v18, 1.0, v18
	v_add_f32_e32 v19, 1.0, v19
	v_rcp_f32_e32 v18, v18
	v_rcp_f32_e32 v19, v19
	v_mul_f32_e32 v18, v18, v24
	v_mul_f32_e32 v19, v19, v25
	v_cvt_pk_bf16_f32 v29, v18, v19
	v_add_u32_e32 v18, 0xa0, v145
	v_mad_i64_i32 v[18:19], s[4:5], v18, s16, v[114:115]
	v_lshl_add_u64 v[18:19], v[18:19], 0, v[116:117]
	global_store_dwordx4 v[18:19], v[26:29], off
	v_exp_f32_e64 v18, -v10
	v_exp_f32_e64 v19, -v11
	v_mul_f32_e32 v10, v10, v14
	v_mul_f32_e32 v11, v11, v15
	v_add_f32_e32 v18, 1.0, v18
	v_add_f32_e32 v19, 1.0, v19
	v_rcp_f32_e32 v18, v18
	v_rcp_f32_e32 v19, v19
	v_mul_f32_e32 v10, v18, v10
	v_mul_f32_e32 v11, v19, v11
	v_cvt_pk_bf16_f32 v10, v10, v11
	v_exp_f32_e64 v11, -v12
	s_nop 0
	v_add_f32_e32 v11, 1.0, v11
	v_rcp_f32_e32 v12, v11
	v_exp_f32_e64 v11, -v13
	s_nop 0
	v_add_f32_e32 v11, 1.0, v11
	v_rcp_f32_e32 v13, v11
	v_mul_f32_e32 v12, v12, v16
	v_mul_f32_e32 v13, v13, v17
	v_cvt_pk_bf16_f32 v11, v12, v13
	v_exp_f32_e64 v12, -v2
	v_exp_f32_e64 v13, -v3
	v_mul_f32_e32 v2, v2, v6
	v_mul_f32_e32 v3, v3, v7
	v_add_f32_e32 v12, 1.0, v12
	v_add_f32_e32 v13, 1.0, v13
	v_rcp_f32_e32 v12, v12
	v_rcp_f32_e32 v13, v13
	v_mul_f32_e32 v2, v12, v2
	v_mul_f32_e32 v3, v13, v3
	v_cvt_pk_bf16_f32 v12, v2, v3
	v_exp_f32_e64 v2, -v4
	v_exp_f32_e64 v3, -v5
	v_add_f32_e32 v2, 1.0, v2
	v_add_f32_e32 v3, 1.0, v3
	v_rcp_f32_e32 v2, v2
	v_rcp_f32_e32 v3, v3
	v_mul_f32_e32 v2, v2, v8
	v_mul_f32_e32 v3, v3, v9
	v_cvt_pk_bf16_f32 v13, v2, v3
	v_add_u32_e32 v2, 0xb0, v145
	v_mad_i64_i32 v[2:3], s[4:5], v2, s16, v[114:115]
	v_lshl_add_u64 v[2:3], v[2:3], 0, v[116:117]
	s_mov_b64 s[4:5], -1
	global_store_dwordx4 v[2:3], v[10:13], off
	s_cbranch_vccnz .LBB0_1660
	s_andn2_b64 vcc, exec, s[36:37]
	s_cbranch_vccnz .LBB0_1659
	s_barrier
	s_branch .LBB0_1659
